# grid barrier: last XCC leader releases all per-XCC generations directly (one poll hop less), ws pointer load hoisted above the arrival s_barrier
# speedup vs baseline: 1.0778x; 1.0086x over previous
.LBB0_517:
	s_cmp_lt_i32 s24, 2
	s_cselect_b64 s[0:1], -1, 0
	s_xor_b64 s[6:7], s[6:7], -1
	s_or_b64 s[0:1], s[0:1], s[6:7]
	s_and_b64 vcc, exec, s[0:1]
	s_cbranch_vccnz .LBB0_5
	s_cmp_lg_u32 s24, 2
	s_mov_b64 s[6:7], -1
	s_cbranch_scc0 .LBB0_526
	s_waitcnt vmcnt(0) lgkmcnt(0)
	v_readlane_b32 s28, v254, 41
	v_readlane_b32 s29, v254, 42
	v_readlane_b32 s0, v254, 28
	s_load_dwordx2 s[28:29], s[28:29], 0x120
	s_add_i32 s13, s0, 1
	s_waitcnt vmcnt(0)
	s_barrier
	s_mov_b64 s[6:7], exec
	v_readlane_b32 s0, v254, 29
	v_readlane_b32 s1, v254, 30
	s_and_b64 s[0:1], s[6:7], s[0:1]
	s_mov_b64 exec, s[0:1]
	s_cbranch_execz .LBB0_525
	s_getreg_b32 s8, hwreg(HW_REG_XCC_ID, 0, 4)
	s_and_b32 s8, s8, 7
	s_lshr_b32 s9, s54, 3
	v_mov_b32_e32 v1, 1
	s_mul_i32 s9, s9, s13
	s_lshl_b32 s11, s8, 4
	s_lshl_b32 s18, s8, 3
	s_add_u32 s18, s18, 0x80
	v_mov_b32_e32 v3, s11
	v_mov_b32_e32 v5, s18
	s_waitcnt lgkmcnt(0)
	s_add_u32 s0, s28, 0x198000
	s_addc_u32 s1, s29, 0
	global_atomic_add v3, v3, v1, s[0:1] sc0
	s_mov_b32 s20, 0
	s_lshl_b32 s21, s13, 3
	s_waitcnt vmcnt(0)
	v_add_u32_e32 v3, 1, v3
	v_cmp_eq_u32_e32 vcc, s9, v3
	s_cbranch_vccz .Lxb_early
	buffer_wbl2 sc1
	s_waitcnt vmcnt(0)
	global_atomic_add v3, v2, v1, s[0:1] offset:192 sc0
	s_waitcnt vmcnt(0)
	v_add_u32_e32 v3, 1, v3
	v_cmp_eq_u32_e32 vcc, s21, v3
	s_cbranch_vccz .Lxb_fspin
	global_atomic_add v2, v1, s[0:1] offset:128
	global_atomic_add v2, v1, s[0:1] offset:136
	global_atomic_add v2, v1, s[0:1] offset:144
	global_atomic_add v2, v1, s[0:1] offset:152
	global_atomic_add v2, v1, s[0:1] offset:160
	global_atomic_add v2, v1, s[0:1] offset:168
	global_atomic_add v2, v1, s[0:1] offset:176
	global_atomic_add v2, v1, s[0:1] offset:184
	s_branch .Lxb_facq
.Lxb_early:
.Lxb_fspin:
	global_load_dword v3, v5, s[0:1] sc1
	s_waitcnt vmcnt(0)
	v_cmp_le_u32_e32 vcc, s13, v3
	s_cbranch_vccnz .Lxb_facq
	s_sleep 1
	s_add_u32 s20, s20, 1
	s_cmp_lt_u32 s20, 0x2000
	s_cbranch_scc1 .Lxb_fspin
	v_mov_b32_e32 v1, 0x100000
	global_atomic_add v2, v1, s[0:1] offset:128
	global_atomic_add v2, v1, s[0:1] offset:136
	global_atomic_add v2, v1, s[0:1] offset:144
	global_atomic_add v2, v1, s[0:1] offset:152
	global_atomic_add v2, v1, s[0:1] offset:160
	global_atomic_add v2, v1, s[0:1] offset:168
	global_atomic_add v2, v1, s[0:1] offset:176
	global_atomic_add v2, v1, s[0:1] offset:184

.LBB0_525:
	s_or_b64 exec, exec, s[6:7]
	s_mov_b64 s[6:7], 0
	s_waitcnt lgkmcnt(0)
	s_barrier
